# P9 K-loop: first-buffer LDS read base adds hoisted out of the loop (no VALU left in the load segments)
# baseline (speedup 1.0000x reference)
.LBB0_1152:
	s_xor_b64 s[48:49], s[54:55], -1
	s_add_u32 s33, s56, 0x100
	s_addc_u32 s72, s57, 0
	s_ashr_i32 s45, s44, 31
	s_lshl_b64 s[50:51], s[44:45], 21
	s_add_u32 s50, s70, s50
	s_addc_u32 s51, s71, s51
	s_and_b64 s[52:53], s[54:55], exec
	s_cselect_b32 s29, s51, s47
	s_cselect_b32 s45, s50, s46
	s_ashr_i32 s43, s42, 31
	s_lshl_b64 s[52:53], s[42:43], 21
	v_readlane_b32 s20, v244, 4
	v_readlane_b32 s21, v244, 5
	s_add_u32 s52, s20, s52
	s_addc_u32 s53, s21, s53
	s_and_b64 s[58:59], s[54:55], exec
	s_cselect_b32 s43, s53, s57
	s_cselect_b32 s73, s52, s56
	v_lshl_add_u64 v[130:131], s[46:47], 0, v[196:197]
	v_lshl_add_u64 v[132:133], s[46:47], 0, v[198:199]
	s_mov_b32 s83, -2
	v_add_u32_e32 v246, 0x18000, v187
	v_add_u32_e32 v247, 0x1c000, v187
	v_add_u32_e32 v248, s78, v187
	v_add_u32_e32 v249, s79, v187
.LBB0_1153:
	s_add_u32 s98, s46, s10
	s_addc_u32 s99, s47, s11
	s_add_u32 s98, s98, 0x100080
	s_addc_u32 s99, s99, 0
	s_add_u32 s56, s46, s10
	ds_read_b128 v[134:137], v248
	ds_read_b128 v[138:141], v248 offset:1024
	ds_read_b128 v[142:145], v248 offset:2048
	ds_read_b128 v[146:149], v248 offset:3072
	ds_read_b128 v[150:153], v249
	ds_read_b128 v[154:157], v249 offset:1024
	ds_read_b128 v[158:161], v249 offset:2048
	ds_read_b128 v[162:165], v249 offset:3072
	s_addc_u32 s57, s47, s11
	s_add_u32 s56, s56, 0x100
	s_addc_u32 s57, s57, 0
	s_add_u32 s84, s33, s10
	s_addc_u32 s85, s72, s11
	s_cmpk_eq_i32 s10, 0x1f00
	s_cselect_b32 s59, s29, s57
	s_cselect_b32 s58, s45, s56
	s_cselect_b32 s57, s43, s85
	s_cselect_b32 s56, s73, s84
	s_add_i32 m0, s64, 0xc000
	ds_read_b128 v[166:169], v230
	ds_read_b128 v[170:173], v230 offset:1024
	ds_read_b128 v[174:177], v230 offset:2048
	ds_read_b128 v[202:205], v230 offset:3072
	ds_read_b128 v[206:209], v230 offset:4096
	ds_read_b128 v[210:213], v230 offset:5120
	ds_read_b128 v[214:217], v230 offset:6144
	ds_read_b128 v[218:221], v230 offset:7168
	global_load_lds_dwordx4 v178, s[98:99]
	s_add_i32 m0, s64, 0xe000
	s_nop 0
	global_load_lds_dwordx4 v182, s[98:99]
	s_waitcnt vmcnt(8)
	s_waitcnt lgkmcnt(0)
	s_barrier
	v_mfma_f32_16x16x32_bf16 v[2:5], v[134:137], v[166:169], v[2:5]
	v_mfma_f32_16x16x32_bf16 v[2:5], v[138:141], v[170:173], v[2:5]
	v_mfma_f32_16x16x32_bf16 v[126:129], v[142:145], v[166:169], v[126:129]
	v_mfma_f32_16x16x32_bf16 v[126:129], v[146:149], v[170:173], v[126:129]
	v_mfma_f32_16x16x32_bf16 v[122:125], v[134:137], v[174:177], v[122:125]
	v_mfma_f32_16x16x32_bf16 v[122:125], v[138:141], v[202:205], v[122:125]
	v_mfma_f32_16x16x32_bf16 v[118:121], v[142:145], v[174:177], v[118:121]
	v_mfma_f32_16x16x32_bf16 v[118:121], v[146:149], v[202:205], v[118:121]
	v_mfma_f32_16x16x32_bf16 v[114:117], v[134:137], v[206:209], v[114:117]
	v_mfma_f32_16x16x32_bf16 v[114:117], v[138:141], v[210:213], v[114:117]
	v_mfma_f32_16x16x32_bf16 v[110:113], v[142:145], v[206:209], v[110:113]
	v_mfma_f32_16x16x32_bf16 v[110:113], v[146:149], v[210:213], v[110:113]
	v_mfma_f32_16x16x32_bf16 v[106:109], v[134:137], v[214:217], v[106:109]
	v_mfma_f32_16x16x32_bf16 v[106:109], v[138:141], v[218:221], v[106:109]
	v_mfma_f32_16x16x32_bf16 v[102:105], v[142:145], v[214:217], v[102:105]
	v_mfma_f32_16x16x32_bf16 v[102:105], v[146:149], v[218:221], v[102:105]
	v_mfma_f32_16x16x32_bf16 v[98:101], v[150:153], v[166:169], v[98:101]
	v_mfma_f32_16x16x32_bf16 v[98:101], v[154:157], v[170:173], v[98:101]
	v_mfma_f32_16x16x32_bf16 v[94:97], v[158:161], v[166:169], v[94:97]
	v_mfma_f32_16x16x32_bf16 v[94:97], v[162:165], v[170:173], v[94:97]
	v_mfma_f32_16x16x32_bf16 v[90:93], v[150:153], v[174:177], v[90:93]
	v_mfma_f32_16x16x32_bf16 v[90:93], v[154:157], v[202:205], v[90:93]
	v_mfma_f32_16x16x32_bf16 v[86:89], v[158:161], v[174:177], v[86:89]
	v_mfma_f32_16x16x32_bf16 v[86:89], v[162:165], v[202:205], v[86:89]
	v_mfma_f32_16x16x32_bf16 v[82:85], v[150:153], v[206:209], v[82:85]
	v_mfma_f32_16x16x32_bf16 v[82:85], v[154:157], v[210:213], v[82:85]
	v_mfma_f32_16x16x32_bf16 v[78:81], v[158:161], v[206:209], v[78:81]
	v_mfma_f32_16x16x32_bf16 v[78:81], v[162:165], v[210:213], v[78:81]
	v_mfma_f32_16x16x32_bf16 v[74:77], v[150:153], v[214:217], v[74:77]
	v_mfma_f32_16x16x32_bf16 v[74:77], v[154:157], v[218:221], v[74:77]
	v_mfma_f32_16x16x32_bf16 v[70:73], v[158:161], v[214:217], v[70:73]
	v_mfma_f32_16x16x32_bf16 v[70:73], v[162:165], v[218:221], v[70:73]
	s_barrier
	s_add_i32 s84, s78, s63
	s_mov_b32 m0, s84
	ds_read_b128 v[166:169], v230 offset:16384
	ds_read_b128 v[170:173], v230 offset:17408
	ds_read_b128 v[174:177], v230 offset:18432
	ds_read_b128 v[202:205], v230 offset:19456
	ds_read_b128 v[206:209], v230 offset:20480
	ds_read_b128 v[210:213], v230 offset:21504
	ds_read_b128 v[214:217], v230 offset:22528
	ds_read_b128 v[218:221], v230 offset:23552
	global_load_lds_dwordx4 v180, s[56:57]
	s_add_i32 m0, s84, 0x2000
	s_add_u32 s84, s56, 0x100000
	s_addc_u32 s85, s57, 0
	s_add_i32 s86, s79, s63
	global_load_lds_dwordx4 v184, s[56:57]
	s_mov_b32 m0, s86
	s_nop 0
	global_load_lds_dwordx4 v180, s[84:85]
	s_add_i32 m0, s86, 0x2000
	s_nop 0
	global_load_lds_dwordx4 v184, s[84:85]
	s_mov_b32 m0, s64
	s_nop 0
	global_load_lds_dwordx4 v178, s[58:59]
	s_mov_b32 m0, s65
	s_nop 0
	global_load_lds_dwordx4 v182, s[58:59]
	s_waitcnt vmcnt(8)
	s_waitcnt lgkmcnt(0)
	s_barrier
	v_mfma_f32_16x16x32_bf16 v[66:69], v[134:137], v[166:169], v[66:69]
	v_mfma_f32_16x16x32_bf16 v[66:69], v[138:141], v[170:173], v[66:69]
	v_mfma_f32_16x16x32_bf16 v[62:65], v[142:145], v[166:169], v[62:65]
	v_mfma_f32_16x16x32_bf16 v[62:65], v[146:149], v[170:173], v[62:65]
	v_mfma_f32_16x16x32_bf16 v[58:61], v[134:137], v[174:177], v[58:61]
	v_mfma_f32_16x16x32_bf16 v[58:61], v[138:141], v[202:205], v[58:61]
	v_mfma_f32_16x16x32_bf16 v[54:57], v[142:145], v[174:177], v[54:57]
	v_mfma_f32_16x16x32_bf16 v[54:57], v[146:149], v[202:205], v[54:57]
	v_mfma_f32_16x16x32_bf16 v[50:53], v[134:137], v[206:209], v[50:53]
	v_mfma_f32_16x16x32_bf16 v[50:53], v[138:141], v[210:213], v[50:53]
	v_mfma_f32_16x16x32_bf16 v[46:49], v[142:145], v[206:209], v[46:49]
	v_mfma_f32_16x16x32_bf16 v[46:49], v[146:149], v[210:213], v[46:49]
	v_mfma_f32_16x16x32_bf16 v[42:45], v[134:137], v[214:217], v[42:45]
	v_mfma_f32_16x16x32_bf16 v[42:45], v[138:141], v[218:221], v[42:45]
	v_mfma_f32_16x16x32_bf16 v[38:41], v[142:145], v[214:217], v[38:41]
	v_mfma_f32_16x16x32_bf16 v[38:41], v[146:149], v[218:221], v[38:41]
	v_mfma_f32_16x16x32_bf16 v[34:37], v[150:153], v[166:169], v[34:37]
	v_mfma_f32_16x16x32_bf16 v[34:37], v[154:157], v[170:173], v[34:37]
	v_mfma_f32_16x16x32_bf16 v[30:33], v[158:161], v[166:169], v[30:33]
	v_mfma_f32_16x16x32_bf16 v[30:33], v[162:165], v[170:173], v[30:33]
	v_mfma_f32_16x16x32_bf16 v[26:29], v[150:153], v[174:177], v[26:29]
	v_mfma_f32_16x16x32_bf16 v[26:29], v[154:157], v[202:205], v[26:29]
	v_mfma_f32_16x16x32_bf16 v[22:25], v[158:161], v[174:177], v[22:25]
	v_mfma_f32_16x16x32_bf16 v[22:25], v[162:165], v[202:205], v[22:25]
	v_mfma_f32_16x16x32_bf16 v[18:21], v[150:153], v[206:209], v[18:21]
	v_mfma_f32_16x16x32_bf16 v[18:21], v[154:157], v[210:213], v[18:21]
	v_mfma_f32_16x16x32_bf16 v[14:17], v[158:161], v[206:209], v[14:17]
	v_mfma_f32_16x16x32_bf16 v[14:17], v[162:165], v[210:213], v[14:17]
	v_mfma_f32_16x16x32_bf16 v[10:13], v[150:153], v[214:217], v[10:13]
	v_mfma_f32_16x16x32_bf16 v[10:13], v[154:157], v[218:221], v[10:13]
	v_mfma_f32_16x16x32_bf16 v[6:9], v[158:161], v[214:217], v[6:9]
	v_mfma_f32_16x16x32_bf16 v[6:9], v[162:165], v[218:221], v[6:9]
	s_barrier
	s_add_i32 s84, 0, 0x18000
	s_add_i32 s85, 0, 0x1c000
	ds_read_b128 v[134:137], v246
	ds_read_b128 v[138:141], v246 offset:1024
	ds_read_b128 v[142:145], v246 offset:2048
	ds_read_b128 v[146:149], v246 offset:3072
	ds_read_b128 v[150:153], v247
	ds_read_b128 v[154:157], v247 offset:1024
	ds_read_b128 v[158:161], v247 offset:2048
	ds_read_b128 v[162:165], v247 offset:3072
	s_add_u32 s100, s58, 0x80
	s_addc_u32 s101, s59, 0
	s_add_u32 s58, s58, 0x100000
	s_addc_u32 s59, s59, 0
	s_mov_b32 m0, s67
	ds_read_b128 v[166:169], v230 offset:32768
	ds_read_b128 v[170:173], v230 offset:33792
	ds_read_b128 v[174:177], v230 offset:34816
	ds_read_b128 v[202:205], v230 offset:35840
	ds_read_b128 v[206:209], v230 offset:36864
	ds_read_b128 v[210:213], v230 offset:37888
	ds_read_b128 v[214:217], v230 offset:38912
	ds_read_b128 v[218:221], v230 offset:39936
	global_load_lds_dwordx4 v178, s[58:59]
	s_mov_b32 m0, s68
	s_nop 0
	global_load_lds_dwordx4 v182, s[58:59]
	s_waitcnt vmcnt(8)
	s_waitcnt lgkmcnt(0)
	s_barrier
	v_mfma_f32_16x16x32_bf16 v[2:5], v[134:137], v[166:169], v[2:5]
	v_mfma_f32_16x16x32_bf16 v[2:5], v[138:141], v[170:173], v[2:5]
	v_mfma_f32_16x16x32_bf16 v[126:129], v[142:145], v[166:169], v[126:129]
	v_mfma_f32_16x16x32_bf16 v[126:129], v[146:149], v[170:173], v[126:129]
	v_mfma_f32_16x16x32_bf16 v[122:125], v[134:137], v[174:177], v[122:125]
	v_mfma_f32_16x16x32_bf16 v[122:125], v[138:141], v[202:205], v[122:125]
	v_mfma_f32_16x16x32_bf16 v[118:121], v[142:145], v[174:177], v[118:121]
	v_mfma_f32_16x16x32_bf16 v[118:121], v[146:149], v[202:205], v[118:121]
	v_mfma_f32_16x16x32_bf16 v[114:117], v[134:137], v[206:209], v[114:117]
	v_mfma_f32_16x16x32_bf16 v[114:117], v[138:141], v[210:213], v[114:117]
	v_mfma_f32_16x16x32_bf16 v[110:113], v[142:145], v[206:209], v[110:113]
	v_mfma_f32_16x16x32_bf16 v[110:113], v[146:149], v[210:213], v[110:113]
	v_mfma_f32_16x16x32_bf16 v[106:109], v[134:137], v[214:217], v[106:109]
	v_mfma_f32_16x16x32_bf16 v[106:109], v[138:141], v[218:221], v[106:109]
	v_mfma_f32_16x16x32_bf16 v[102:105], v[142:145], v[214:217], v[102:105]
	v_mfma_f32_16x16x32_bf16 v[102:105], v[146:149], v[218:221], v[102:105]
	v_mfma_f32_16x16x32_bf16 v[98:101], v[150:153], v[166:169], v[98:101]
	v_mfma_f32_16x16x32_bf16 v[98:101], v[154:157], v[170:173], v[98:101]
	v_mfma_f32_16x16x32_bf16 v[94:97], v[158:161], v[166:169], v[94:97]
	v_mfma_f32_16x16x32_bf16 v[94:97], v[162:165], v[170:173], v[94:97]
	v_mfma_f32_16x16x32_bf16 v[90:93], v[150:153], v[174:177], v[90:93]
	v_mfma_f32_16x16x32_bf16 v[90:93], v[154:157], v[202:205], v[90:93]
	v_mfma_f32_16x16x32_bf16 v[86:89], v[158:161], v[174:177], v[86:89]
	v_mfma_f32_16x16x32_bf16 v[86:89], v[162:165], v[202:205], v[86:89]
	v_mfma_f32_16x16x32_bf16 v[82:85], v[150:153], v[206:209], v[82:85]
	v_mfma_f32_16x16x32_bf16 v[82:85], v[154:157], v[210:213], v[82:85]
	v_mfma_f32_16x16x32_bf16 v[78:81], v[158:161], v[206:209], v[78:81]
	v_mfma_f32_16x16x32_bf16 v[78:81], v[162:165], v[210:213], v[78:81]
	v_mfma_f32_16x16x32_bf16 v[74:77], v[150:153], v[214:217], v[74:77]
	v_mfma_f32_16x16x32_bf16 v[74:77], v[154:157], v[218:221], v[74:77]
	v_mfma_f32_16x16x32_bf16 v[70:73], v[158:161], v[214:217], v[70:73]
	v_mfma_f32_16x16x32_bf16 v[70:73], v[162:165], v[218:221], v[70:73]
	s_barrier
	s_add_i32 s58, s84, s63
	s_add_u32 s98, s56, 0x80
	s_addc_u32 s99, s57, 0
	s_mov_b32 m0, s58
	ds_read_b128 v[166:169], v230 offset:49152
	ds_read_b128 v[170:173], v230 offset:50176
	ds_read_b128 v[174:177], v230 offset:51200
	ds_read_b128 v[202:205], v230 offset:52224
	ds_read_b128 v[206:209], v230 offset:53248
	ds_read_b128 v[210:213], v230 offset:54272
	ds_read_b128 v[214:217], v230 offset:55296
	ds_read_b128 v[218:221], v230 offset:56320
	global_load_lds_dwordx4 v180, s[98:99]
	s_add_i32 m0, s58, 0x2000
	s_add_u32 s56, s56, 0x100080
	s_addc_u32 s57, s57, 0
	s_add_i32 s58, s85, s63
	global_load_lds_dwordx4 v184, s[98:99]
	s_mov_b32 m0, s58
	s_nop 0
	global_load_lds_dwordx4 v180, s[56:57]
	s_add_i32 m0, s58, 0x2000
	s_nop 0
	global_load_lds_dwordx4 v184, s[56:57]
	s_mov_b32 m0, s74
	s_nop 0
	global_load_lds_dwordx4 v178, s[100:101]
	s_mov_b32 m0, s75
	s_nop 0
	global_load_lds_dwordx4 v182, s[100:101]
	s_waitcnt vmcnt(8)
	s_waitcnt lgkmcnt(0)
	s_barrier
	v_mfma_f32_16x16x32_bf16 v[66:69], v[134:137], v[166:169], v[66:69]
	v_mfma_f32_16x16x32_bf16 v[66:69], v[138:141], v[170:173], v[66:69]
	v_mfma_f32_16x16x32_bf16 v[62:65], v[142:145], v[166:169], v[62:65]
	v_mfma_f32_16x16x32_bf16 v[62:65], v[146:149], v[170:173], v[62:65]
	v_mfma_f32_16x16x32_bf16 v[58:61], v[134:137], v[174:177], v[58:61]
	v_mfma_f32_16x16x32_bf16 v[58:61], v[138:141], v[202:205], v[58:61]
	v_mfma_f32_16x16x32_bf16 v[54:57], v[142:145], v[174:177], v[54:57]
	v_mfma_f32_16x16x32_bf16 v[54:57], v[146:149], v[202:205], v[54:57]
	v_mfma_f32_16x16x32_bf16 v[50:53], v[134:137], v[206:209], v[50:53]
	v_mfma_f32_16x16x32_bf16 v[50:53], v[138:141], v[210:213], v[50:53]
	v_mfma_f32_16x16x32_bf16 v[46:49], v[142:145], v[206:209], v[46:49]
	v_mfma_f32_16x16x32_bf16 v[46:49], v[146:149], v[210:213], v[46:49]
	v_mfma_f32_16x16x32_bf16 v[42:45], v[134:137], v[214:217], v[42:45]
	v_mfma_f32_16x16x32_bf16 v[42:45], v[138:141], v[218:221], v[42:45]
	v_mfma_f32_16x16x32_bf16 v[38:41], v[142:145], v[214:217], v[38:41]
	v_mfma_f32_16x16x32_bf16 v[38:41], v[146:149], v[218:221], v[38:41]
	v_mfma_f32_16x16x32_bf16 v[34:37], v[150:153], v[166:169], v[34:37]
	v_mfma_f32_16x16x32_bf16 v[34:37], v[154:157], v[170:173], v[34:37]
	v_mfma_f32_16x16x32_bf16 v[30:33], v[158:161], v[166:169], v[30:33]
	v_mfma_f32_16x16x32_bf16 v[30:33], v[162:165], v[170:173], v[30:33]
	v_mfma_f32_16x16x32_bf16 v[26:29], v[150:153], v[174:177], v[26:29]
	v_mfma_f32_16x16x32_bf16 v[26:29], v[154:157], v[202:205], v[26:29]
	v_mfma_f32_16x16x32_bf16 v[22:25], v[158:161], v[174:177], v[22:25]
	v_mfma_f32_16x16x32_bf16 v[22:25], v[162:165], v[202:205], v[22:25]
	v_mfma_f32_16x16x32_bf16 v[18:21], v[150:153], v[206:209], v[18:21]
	v_mfma_f32_16x16x32_bf16 v[18:21], v[154:157], v[210:213], v[18:21]
	v_mfma_f32_16x16x32_bf16 v[14:17], v[158:161], v[206:209], v[14:17]
	v_mfma_f32_16x16x32_bf16 v[14:17], v[162:165], v[210:213], v[14:17]
	v_mfma_f32_16x16x32_bf16 v[10:13], v[150:153], v[214:217], v[10:13]
	v_mfma_f32_16x16x32_bf16 v[10:13], v[154:157], v[218:221], v[10:13]
	v_mfma_f32_16x16x32_bf16 v[6:9], v[158:161], v[214:217], v[6:9]
	v_mfma_f32_16x16x32_bf16 v[6:9], v[162:165], v[218:221], v[6:9]
	s_barrier
	s_add_i32 s83, s83, 2
	s_add_u32 s10, s10, 0x100
	s_addc_u32 s11, s11, 0
	s_cmp_gt_u32 s83, 61
	s_cbranch_scc0 .LBB0_1153
	s_and_b64 vcc, exec, s[36:37]
	s_cbranch_vccz .LBB0_1156
	s_barrier
